# rw_item pass-1 token loop: output (o) lane reduction of token k deferred and interleaved with the state-dot reduction of token k+1 (bit-identical), LDS waits re-derived
# speedup vs baseline: 1.0042x; 1.0042x over previous
; #define LAS __attribute__((address_space(3)))
; template <int pass>
; __device__ __forceinline__ void rw_item(const Params& p, int l, int seg, int h, LAS float* sm, int tid, int lane, int wave) {
;     ...
;         for (int t = 0; t < TS; ++t) {
;             const f32x4 w4 = nw4, k4 = nk4, a4 = na4, b4 = nb4, q4 = nq4; const f32x2 vv = nvv;
;             {
;                 const int tn = (t + 1 < TS) ? t + 1 : t, on = tn * 64 + kq * 4;
;                 nw4 = *(const LAS f32x4*)(bf + 1024 + on); nk4 = *(const LAS f32x4*)(bf + 2048 + on);
;                 na4 = *(const LAS f32x4*)(bf + 3072 + on); nb4 = *(const LAS f32x4*)(bf + 4096 + on);
;                 nvv = *(const LAS f32x2*)(bf + 5120 + tn * 64 + j0);
;                 if (pass == 1) nq4 = *(const LAS f32x4*)(bf + on);
;             }
;             const f32x2 vA = {vv.x, vv.x}, vB = {vv.y, vv.y};
;             f32x2 ua = b4.xy * sA[0], ub = b4.xy * sB[0];
;             ua = b4.zw * sA[1] + ua; ub = b4.zw * sB[1] + ub;
;             float uA = ua.x + ua.y, uB = ub.x + ub.y, gA = 0.f, gB = 0.f;
;             if (pass == 0) {
;                 f32x2 qa = b4.xy * pA[0], qb = b4.xy * pB[0];
;                 qa = b4.zw * pA[1] + qa; qb = b4.zw * pB[1] + qb;
;                 gA = qa.x + qa.y; gB = qb.x + qb.y;
;                 kq_sum16x4(uA, uB, gA, gB);
;             } else { uA = kq_sum<16>(uA); uB = kq_sum<16>(uB); }
;             const f32x2 uA2 = {uA, uA}, uB2 = {uB, uB};
;             { const f32x2 t0_ = k4.xy * vA - a4.xy * uA2, t1_ = k4.zw * vA - a4.zw * uA2; sA[0] = w4.xy * sA[0] + t0_; sA[1] = w4.zw * sA[1] + t1_; }
;             { const f32x2 t0_ = k4.xy * vB - a4.xy * uB2, t1_ = k4.zw * vB - a4.zw * uB2; sB[0] = w4.xy * sB[0] + t0_; sB[1] = w4.zw * sB[1] + t1_; }
;             if (pass == 0) {
;                 const f32x2 gA2 = {gA, gA}, gB2 = {gB, gB};
;                 pA[0] = w4.xy * pA[0] - a4.xy * gA2; pA[1] = w4.zw * pA[1] - a4.zw * gA2;
;                 pB[0] = w4.xy * pB[0] - a4.xy * gB2; pB[1] = w4.zw * pB[1] - a4.zw * gB2;
;             } else {
;                 f32x2 oa = q4.xy * sA[0], ob2 = q4.xy * sB[0];
;                 oa = q4.zw * sA[1] + oa; ob2 = q4.zw * sB[1] + ob2;
;                 const float oA = kq_sum<16>(oa.x + oa.y), oB = kq_sum<16>(ob2.x + ob2.y);
;                 if (kq == 0) *(LAS f32x2*)(ob + t * 64 + j0) = (f32x2){oA, oB};
;             }
.LBB0_457:
	s_waitcnt lgkmcnt(2)
	v_pk_mul_f32 v[52:53], v[28:29], v[8:9]
	v_pk_mul_f32 v[28:29], v[28:29], v[4:5]
	v_pk_fma_f32 v[52:53], v[26:27], v[6:7], v[52:53]
	v_pk_fma_f32 v[26:27], v[26:27], v[2:3], v[28:29]
	v_add_f32_e32 v28, v52, v53
	v_add_f32_e32 v27, v26, v27
	v_add_u32_e32 v97, s38, v94
	v_add_f32_dpp v26, v28, v28 quad_perm:[1,0,3,2] row_mask:0xf bank_mask:0xf bound_ctrl:1
	v_add_f32_dpp v27, v27, v27 quad_perm:[1,0,3,2] row_mask:0xf bank_mask:0xf bound_ctrl:1
	ds_read_b128 v[34:37], v97 offset:8192
	ds_read_b128 v[38:41], v97 offset:12288
	v_add_f32_dpp v26, v26, v26 quad_perm:[2,3,0,1] row_mask:0xf bank_mask:0xf bound_ctrl:1
	v_add_f32_dpp v27, v27, v27 quad_perm:[2,3,0,1] row_mask:0xf bank_mask:0xf bound_ctrl:1
	v_add_u32_e32 v98, s38, v92
	v_add_f32_dpp v26, v26, v26 row_half_mirror row_mask:0xf bank_mask:0xf bound_ctrl:1
	v_add_f32_dpp v27, v27, v27 row_half_mirror row_mask:0xf bank_mask:0xf bound_ctrl:1
	ds_read_b128 v[46:49], v97 offset:16384
	ds_read_b64 v[66:67], v98
	ds_read_b128 v[42:45], v97 offset:4096
	ds_read_b128 v[30:33], v97
	v_add_f32_dpp v26, v26, v26 row_mirror row_mask:0xf bank_mask:0xf bound_ctrl:1
	v_add_f32_dpp v28, v27, v27 row_mirror row_mask:0xf bank_mask:0xf bound_ctrl:1
	v_pk_mul_f32 v[52:53], v[18:19], v[26:27] op_sel_hi:[1,0]
	v_pk_mul_f32 v[18:19], v[18:19], v[28:29] op_sel_hi:[1,0]
	s_waitcnt lgkmcnt(7)
	v_pk_fma_f32 v[52:53], v[14:15], v[50:51], v[52:53] op_sel_hi:[1,0,1] neg_lo:[0,0,1] neg_hi:[0,0,1]
	v_pk_mul_f32 v[26:27], v[20:21], v[26:27] op_sel_hi:[1,0]
	v_pk_fma_f32 v[14:15], v[14:15], v[50:51], v[18:19] op_sel:[0,1,0] neg_lo:[0,0,1] neg_hi:[0,0,1]
	v_pk_mul_f32 v[18:19], v[20:21], v[28:29] op_sel_hi:[1,0]
	v_pk_fma_f32 v[26:27], v[16:17], v[50:51], v[26:27] op_sel_hi:[1,0,1] neg_lo:[0,0,1] neg_hi:[0,0,1]
	v_pk_fma_f32 v[6:7], v[10:11], v[6:7], v[52:53]
	v_pk_fma_f32 v[16:17], v[16:17], v[50:51], v[18:19] op_sel:[0,1,0] neg_lo:[0,0,1] neg_hi:[0,0,1]
	v_pk_fma_f32 v[14:15], v[10:11], v[2:3], v[14:15]
	v_pk_fma_f32 v[8:9], v[12:13], v[8:9], v[26:27]
	v_pk_fma_f32 v[16:17], v[12:13], v[4:5], v[16:17]
	s_waitcnt lgkmcnt(6)
	v_pk_mul_f32 v[2:3], v[22:23], v[6:7]
	v_pk_mul_f32 v[4:5], v[22:23], v[14:15]
	v_pk_fma_f32 v[2:3], v[24:25], v[8:9], v[2:3]
	v_pk_fma_f32 v[4:5], v[24:25], v[16:17], v[4:5]
	v_add_f32_e32 v100, v2, v3
	v_add_f32_e32 v101, v4, v5
	v_add_u32_e32 v96, s38, v95
	s_waitcnt lgkmcnt(2)
	v_pk_mul_f32 v[26:27], v[48:49], v[8:9]
	v_pk_mul_f32 v[28:29], v[48:49], v[16:17]
	v_pk_fma_f32 v[26:27], v[46:47], v[6:7], v[26:27]
	v_pk_fma_f32 v[28:29], v[46:47], v[14:15], v[28:29]
	v_add_f32_e32 v26, v26, v27
	v_add_f32_e32 v27, v28, v29
	ds_read_b128 v[10:13], v97 offset:8448
	ds_read_b128 v[22:25], v97 offset:12544
	ds_read_b128 v[50:53], v97 offset:16640
	ds_read_b64 v[68:69], v98 offset:256
	ds_read_b128 v[18:21], v97 offset:4352
	ds_read_b128 v[2:5], v97 offset:256
	v_add_f32_dpp v26, v26, v26 quad_perm:[1,0,3,2] row_mask:0xf bank_mask:0xf bound_ctrl:1
	v_add_f32_dpp v27, v27, v27 quad_perm:[1,0,3,2] row_mask:0xf bank_mask:0xf bound_ctrl:1
	v_add_f32_dpp v100, v100, v100 quad_perm:[1,0,3,2] row_mask:0xf bank_mask:0xf bound_ctrl:1
	v_add_f32_dpp v101, v101, v101 quad_perm:[1,0,3,2] row_mask:0xf bank_mask:0xf bound_ctrl:1
	v_add_f32_dpp v26, v26, v26 quad_perm:[2,3,0,1] row_mask:0xf bank_mask:0xf bound_ctrl:1
	v_add_f32_dpp v27, v27, v27 quad_perm:[2,3,0,1] row_mask:0xf bank_mask:0xf bound_ctrl:1
	v_add_f32_dpp v100, v100, v100 quad_perm:[2,3,0,1] row_mask:0xf bank_mask:0xf bound_ctrl:1
	v_add_f32_dpp v101, v101, v101 quad_perm:[2,3,0,1] row_mask:0xf bank_mask:0xf bound_ctrl:1
	v_add_f32_dpp v26, v26, v26 row_half_mirror row_mask:0xf bank_mask:0xf bound_ctrl:1
	v_add_f32_dpp v27, v27, v27 row_half_mirror row_mask:0xf bank_mask:0xf bound_ctrl:1
	v_add_f32_dpp v100, v100, v100 row_half_mirror row_mask:0xf bank_mask:0xf bound_ctrl:1
	v_add_f32_dpp v101, v101, v101 row_half_mirror row_mask:0xf bank_mask:0xf bound_ctrl:1
	v_add_f32_dpp v26, v26, v26 row_mirror row_mask:0xf bank_mask:0xf bound_ctrl:1
	v_pk_mul_f32 v[46:47], v[38:39], v[26:27] op_sel_hi:[1,0]
	v_add_f32_dpp v28, v27, v27 row_mirror row_mask:0xf bank_mask:0xf bound_ctrl:1
	v_add_f32_dpp v100, v100, v100 row_mirror row_mask:0xf bank_mask:0xf bound_ctrl:1
	v_add_f32_dpp v101, v101, v101 row_mirror row_mask:0xf bank_mask:0xf bound_ctrl:1
	s_mov_b64 exec, vcc
	ds_write_b64 v96, v[100:101]
	s_mov_b64 exec, -1
	s_waitcnt lgkmcnt(8)
	v_pk_fma_f32 v[46:47], v[34:35], v[66:67], v[46:47] op_sel_hi:[1,0,1] neg_lo:[0,0,1] neg_hi:[0,0,1]
	v_pk_mul_f32 v[26:27], v[40:41], v[26:27] op_sel_hi:[1,0]
	s_waitcnt lgkmcnt(7)
	v_pk_fma_f32 v[46:47], v[42:43], v[6:7], v[46:47]
	v_pk_fma_f32 v[26:27], v[36:37], v[66:67], v[26:27] op_sel_hi:[1,0,1] neg_lo:[0,0,1] neg_hi:[0,0,1]
	v_pk_mul_f32 v[6:7], v[38:39], v[28:29] op_sel_hi:[1,0]
	v_pk_fma_f32 v[48:49], v[44:45], v[8:9], v[26:27]
	v_pk_fma_f32 v[6:7], v[34:35], v[66:67], v[6:7] op_sel:[0,1,0] neg_lo:[0,0,1] neg_hi:[0,0,1]
	v_pk_mul_f32 v[8:9], v[40:41], v[28:29] op_sel_hi:[1,0]
	v_pk_fma_f32 v[38:39], v[42:43], v[14:15], v[6:7]
	v_pk_fma_f32 v[8:9], v[36:37], v[66:67], v[8:9] op_sel:[0,1,0] neg_lo:[0,0,1] neg_hi:[0,0,1]
	s_waitcnt lgkmcnt(7)
	v_pk_mul_f32 v[6:7], v[30:31], v[46:47]
	v_pk_fma_f32 v[40:41], v[44:45], v[16:17], v[8:9]
	v_pk_mul_f32 v[8:9], v[30:31], v[38:39]
	v_pk_fma_f32 v[6:7], v[32:33], v[48:49], v[6:7]
	v_pk_fma_f32 v[8:9], v[32:33], v[40:41], v[8:9]
	v_add_f32_e32 v100, v6, v7
	v_add_f32_e32 v101, v8, v9
	s_waitcnt lgkmcnt(3)
; #define LAS __attribute__((address_space(3)))
; template <int pass>
; __device__ __forceinline__ void rw_item(const Params& p, int l, int seg, int h, LAS float* sm, int tid, int lane, int wave) {
;     ...
;         for (int t = 0; t < TS; ++t) {
;             const f32x4 w4 = nw4, k4 = nk4, a4 = na4, b4 = nb4, q4 = nq4; const f32x2 vv = nvv;
;             {
;                 const int tn = (t + 1 < TS) ? t + 1 : t, on = tn * 64 + kq * 4;
;                 nw4 = *(const LAS f32x4*)(bf + 1024 + on); nk4 = *(const LAS f32x4*)(bf + 2048 + on);
;                 na4 = *(const LAS f32x4*)(bf + 3072 + on); nb4 = *(const LAS f32x4*)(bf + 4096 + on);
;                 nvv = *(const LAS f32x2*)(bf + 5120 + tn * 64 + j0);
;                 if (pass == 1) nq4 = *(const LAS f32x4*)(bf + on);
;             }
;             const f32x2 vA = {vv.x, vv.x}, vB = {vv.y, vv.y};
;             f32x2 ua = b4.xy * sA[0], ub = b4.xy * sB[0];
;             ua = b4.zw * sA[1] + ua; ub = b4.zw * sB[1] + ub;
;             float uA = ua.x + ua.y, uB = ub.x + ub.y, gA = 0.f, gB = 0.f;
;             if (pass == 0) {
;                 f32x2 qa = b4.xy * pA[0], qb = b4.xy * pB[0];
;                 qa = b4.zw * pA[1] + qa; qb = b4.zw * pB[1] + qb;
;                 gA = qa.x + qa.y; gB = qb.x + qb.y;
;                 kq_sum16x4(uA, uB, gA, gB);
;             } else { uA = kq_sum<16>(uA); uB = kq_sum<16>(uB); }
;             const f32x2 uA2 = {uA, uA}, uB2 = {uB, uB};
;             { const f32x2 t0_ = k4.xy * vA - a4.xy * uA2, t1_ = k4.zw * vA - a4.zw * uA2; sA[0] = w4.xy * sA[0] + t0_; sA[1] = w4.zw * sA[1] + t1_; }
;             { const f32x2 t0_ = k4.xy * vB - a4.xy * uB2, t1_ = k4.zw * vB - a4.zw * uB2; sB[0] = w4.xy * sB[0] + t0_; sB[1] = w4.zw * sB[1] + t1_; }
;             if (pass == 0) {
;                 const f32x2 gA2 = {gA, gA}, gB2 = {gB, gB};
;                 pA[0] = w4.xy * pA[0] - a4.xy * gA2; pA[1] = w4.zw * pA[1] - a4.zw * gA2;
;                 pB[0] = w4.xy * pB[0] - a4.xy * gB2; pB[1] = w4.zw * pB[1] - a4.zw * gB2;
;             } else {
;                 f32x2 oa = q4.xy * sA[0], ob2 = q4.xy * sB[0];
;                 oa = q4.zw * sA[1] + oa; ob2 = q4.zw * sB[1] + ob2;
;                 const float oA = kq_sum<16>(oa.x + oa.y), oB = kq_sum<16>(ob2.x + ob2.y);
;                 if (kq == 0) *(LAS f32x2*)(ob + t * 64 + j0) = (f32x2){oA, oB};
;             }
	v_pk_mul_f32 v[44:45], v[52:53], v[48:49]
	v_pk_mul_f32 v[52:53], v[52:53], v[40:41]
	v_pk_fma_f32 v[44:45], v[50:51], v[46:47], v[44:45]
	v_pk_fma_f32 v[50:51], v[50:51], v[38:39], v[52:53]
	v_add_f32_e32 v44, v44, v45
	v_add_f32_e32 v45, v50, v51
	ds_read_b128 v[14:17], v97 offset:8704
	ds_read_b128 v[30:33], v97 offset:12800
	ds_read_b128 v[34:37], v97 offset:16896
	ds_read_b64 v[42:43], v98 offset:512
	ds_read_b128 v[26:29], v97 offset:4608
	ds_read_b128 v[6:9], v97 offset:512
	v_add_f32_dpp v44, v44, v44 quad_perm:[1,0,3,2] row_mask:0xf bank_mask:0xf bound_ctrl:1
	v_add_f32_dpp v45, v45, v45 quad_perm:[1,0,3,2] row_mask:0xf bank_mask:0xf bound_ctrl:1
	v_add_f32_dpp v100, v100, v100 quad_perm:[1,0,3,2] row_mask:0xf bank_mask:0xf bound_ctrl:1
	v_add_f32_dpp v101, v101, v101 quad_perm:[1,0,3,2] row_mask:0xf bank_mask:0xf bound_ctrl:1
	v_add_f32_dpp v44, v44, v44 quad_perm:[2,3,0,1] row_mask:0xf bank_mask:0xf bound_ctrl:1
	v_add_f32_dpp v45, v45, v45 quad_perm:[2,3,0,1] row_mask:0xf bank_mask:0xf bound_ctrl:1
	v_add_f32_dpp v100, v100, v100 quad_perm:[2,3,0,1] row_mask:0xf bank_mask:0xf bound_ctrl:1
	v_add_f32_dpp v101, v101, v101 quad_perm:[2,3,0,1] row_mask:0xf bank_mask:0xf bound_ctrl:1
	v_add_f32_dpp v44, v44, v44 row_half_mirror row_mask:0xf bank_mask:0xf bound_ctrl:1
	v_add_f32_dpp v45, v45, v45 row_half_mirror row_mask:0xf bank_mask:0xf bound_ctrl:1
	v_add_f32_dpp v100, v100, v100 row_half_mirror row_mask:0xf bank_mask:0xf bound_ctrl:1
	v_add_f32_dpp v101, v101, v101 row_half_mirror row_mask:0xf bank_mask:0xf bound_ctrl:1
	v_add_f32_dpp v44, v44, v44 row_mirror row_mask:0xf bank_mask:0xf bound_ctrl:1
	v_add_f32_dpp v50, v45, v45 row_mirror row_mask:0xf bank_mask:0xf bound_ctrl:1
	v_add_f32_dpp v100, v100, v100 row_mirror row_mask:0xf bank_mask:0xf bound_ctrl:1
	v_add_f32_dpp v101, v101, v101 row_mirror row_mask:0xf bank_mask:0xf bound_ctrl:1
	s_mov_b64 exec, vcc
	ds_write_b64 v96, v[100:101] offset:256
	s_mov_b64 exec, -1
	v_pk_mul_f32 v[52:53], v[22:23], v[44:45] op_sel_hi:[1,0]
	v_pk_mul_f32 v[22:23], v[22:23], v[50:51] op_sel_hi:[1,0]
	s_waitcnt lgkmcnt(9)
	v_pk_fma_f32 v[52:53], v[10:11], v[68:69], v[52:53] op_sel_hi:[1,0,1] neg_lo:[0,0,1] neg_hi:[0,0,1]
	v_pk_mul_f32 v[44:45], v[24:25], v[44:45] op_sel_hi:[1,0]
	v_pk_fma_f32 v[10:11], v[10:11], v[68:69], v[22:23] op_sel:[0,1,0] neg_lo:[0,0,1] neg_hi:[0,0,1]
	v_pk_mul_f32 v[22:23], v[24:25], v[50:51] op_sel_hi:[1,0]
	v_pk_fma_f32 v[44:45], v[12:13], v[68:69], v[44:45] op_sel_hi:[1,0,1] neg_lo:[0,0,1] neg_hi:[0,0,1]
	s_waitcnt lgkmcnt(8)
	v_pk_fma_f32 v[46:47], v[18:19], v[46:47], v[52:53]
	v_pk_fma_f32 v[12:13], v[12:13], v[68:69], v[22:23] op_sel:[0,1,0] neg_lo:[0,0,1] neg_hi:[0,0,1]
	v_pk_fma_f32 v[50:51], v[18:19], v[38:39], v[10:11]
	v_pk_fma_f32 v[48:49], v[20:21], v[48:49], v[44:45]
	v_pk_fma_f32 v[52:53], v[20:21], v[40:41], v[12:13]
	s_waitcnt lgkmcnt(8)
	v_pk_mul_f32 v[10:11], v[2:3], v[46:47]
	v_pk_mul_f32 v[2:3], v[2:3], v[50:51]
	v_pk_fma_f32 v[10:11], v[4:5], v[48:49], v[10:11]
	v_pk_fma_f32 v[2:3], v[4:5], v[52:53], v[2:3]
	v_add_f32_e32 v101, v2, v3
	v_add_f32_e32 v100, v10, v11
	s_waitcnt lgkmcnt(3)
	v_pk_mul_f32 v[66:67], v[36:37], v[48:49]
	v_pk_mul_f32 v[36:37], v[36:37], v[52:53]
	v_pk_fma_f32 v[66:67], v[34:35], v[46:47], v[66:67]
	v_pk_fma_f32 v[34:35], v[34:35], v[50:51], v[36:37]
	v_add_f32_e32 v36, v66, v67
	v_add_f32_e32 v35, v34, v35
	ds_read_b128 v[10:13], v97 offset:8960
	ds_read_b128 v[22:25], v97 offset:13056
	ds_read_b128 v[38:41], v97 offset:17152
	ds_read_b64 v[44:45], v98 offset:768
	ds_read_b128 v[18:21], v97 offset:4864
	ds_read_b128 v[2:5], v97 offset:768
	v_add_f32_dpp v34, v36, v36 quad_perm:[1,0,3,2] row_mask:0xf bank_mask:0xf bound_ctrl:1
	v_add_f32_dpp v35, v35, v35 quad_perm:[1,0,3,2] row_mask:0xf bank_mask:0xf bound_ctrl:1
	v_add_f32_dpp v100, v100, v100 quad_perm:[1,0,3,2] row_mask:0xf bank_mask:0xf bound_ctrl:1
	v_add_f32_dpp v101, v101, v101 quad_perm:[1,0,3,2] row_mask:0xf bank_mask:0xf bound_ctrl:1
	v_add_f32_dpp v34, v34, v34 quad_perm:[2,3,0,1] row_mask:0xf bank_mask:0xf bound_ctrl:1
	v_add_f32_dpp v35, v35, v35 quad_perm:[2,3,0,1] row_mask:0xf bank_mask:0xf bound_ctrl:1
	v_add_f32_dpp v100, v100, v100 quad_perm:[2,3,0,1] row_mask:0xf bank_mask:0xf bound_ctrl:1
	v_add_f32_dpp v101, v101, v101 quad_perm:[2,3,0,1] row_mask:0xf bank_mask:0xf bound_ctrl:1
	v_add_f32_dpp v34, v34, v34 row_half_mirror row_mask:0xf bank_mask:0xf bound_ctrl:1
	v_add_f32_dpp v35, v35, v35 row_half_mirror row_mask:0xf bank_mask:0xf bound_ctrl:1
	v_add_f32_dpp v100, v100, v100 row_half_mirror row_mask:0xf bank_mask:0xf bound_ctrl:1
	v_add_f32_dpp v101, v101, v101 row_half_mirror row_mask:0xf bank_mask:0xf bound_ctrl:1
	v_add_f32_dpp v34, v34, v34 row_mirror row_mask:0xf bank_mask:0xf bound_ctrl:1
	v_add_f32_dpp v36, v35, v35 row_mirror row_mask:0xf bank_mask:0xf bound_ctrl:1
	v_add_f32_dpp v100, v100, v100 row_mirror row_mask:0xf bank_mask:0xf bound_ctrl:1
	v_add_f32_dpp v101, v101, v101 row_mirror row_mask:0xf bank_mask:0xf bound_ctrl:1
	s_mov_b64 exec, vcc
	ds_write_b64 v96, v[100:101] offset:512
	s_mov_b64 exec, -1
	v_pk_mul_f32 v[66:67], v[30:31], v[34:35] op_sel_hi:[1,0]
	v_pk_mul_f32 v[30:31], v[30:31], v[36:37] op_sel_hi:[1,0]
	s_waitcnt lgkmcnt(9)
	v_pk_fma_f32 v[66:67], v[14:15], v[42:43], v[66:67] op_sel_hi:[1,0,1] neg_lo:[0,0,1] neg_hi:[0,0,1]
	v_pk_mul_f32 v[34:35], v[32:33], v[34:35] op_sel_hi:[1,0]
	v_pk_fma_f32 v[14:15], v[14:15], v[42:43], v[30:31] op_sel:[0,1,0] neg_lo:[0,0,1] neg_hi:[0,0,1]
	v_pk_mul_f32 v[30:31], v[32:33], v[36:37] op_sel_hi:[1,0]
	v_pk_fma_f32 v[34:35], v[16:17], v[42:43], v[34:35] op_sel_hi:[1,0,1] neg_lo:[0,0,1] neg_hi:[0,0,1]
	s_waitcnt lgkmcnt(8)
; #define LAS __attribute__((address_space(3)))
; template <int pass>
; __device__ __forceinline__ void rw_item(const Params& p, int l, int seg, int h, LAS float* sm, int tid, int lane, int wave) {
;     ...
;                 const int tn = (t + 1 < TS) ? t + 1 : t, on = tn * 64 + kq * 4;
;                 nw4 = *(const LAS f32x4*)(bf + 1024 + on); nk4 = *(const LAS f32x4*)(bf + 2048 + on);
;                 na4 = *(const LAS f32x4*)(bf + 3072 + on); nb4 = *(const LAS f32x4*)(bf + 4096 + on);
;                 nvv = *(const LAS f32x2*)(bf + 5120 + tn * 64 + j0);
;                 if (pass == 1) nq4 = *(const LAS f32x4*)(bf + on);
;             }
;             const f32x2 vA = {vv.x, vv.x}, vB = {vv.y, vv.y};
;             f32x2 ua = b4.xy * sA[0], ub = b4.xy * sB[0];
;             ua = b4.zw * sA[1] + ua; ub = b4.zw * sB[1] + ub;
;             float uA = ua.x + ua.y, uB = ub.x + ub.y, gA = 0.f, gB = 0.f;
;             if (pass == 0) {
;                 f32x2 qa = b4.xy * pA[0], qb = b4.xy * pB[0];
;                 qa = b4.zw * pA[1] + qa; qb = b4.zw * pB[1] + qb;
;                 gA = qa.x + qa.y; gB = qb.x + qb.y;
;                 kq_sum16x4(uA, uB, gA, gB);
;             } else { uA = kq_sum<16>(uA); uB = kq_sum<16>(uB); }
;             const f32x2 uA2 = {uA, uA}, uB2 = {uB, uB};
;             { const f32x2 t0_ = k4.xy * vA - a4.xy * uA2, t1_ = k4.zw * vA - a4.zw * uA2; sA[0] = w4.xy * sA[0] + t0_; sA[1] = w4.zw * sA[1] + t1_; }
;             { const f32x2 t0_ = k4.xy * vB - a4.xy * uB2, t1_ = k4.zw * vB - a4.zw * uB2; sB[0] = w4.xy * sB[0] + t0_; sB[1] = w4.zw * sB[1] + t1_; }
;             if (pass == 0) {
;                 const f32x2 gA2 = {gA, gA}, gB2 = {gB, gB};
;                 pA[0] = w4.xy * pA[0] - a4.xy * gA2; pA[1] = w4.zw * pA[1] - a4.zw * gA2;
;                 pB[0] = w4.xy * pB[0] - a4.xy * gB2; pB[1] = w4.zw * pB[1] - a4.zw * gB2;
;             } else {
;                 f32x2 oa = q4.xy * sA[0], ob2 = q4.xy * sB[0];
;                 oa = q4.zw * sA[1] + oa; ob2 = q4.zw * sB[1] + ob2;
;                 const float oA = kq_sum<16>(oa.x + oa.y), oB = kq_sum<16>(ob2.x + ob2.y);
;                 if (kq == 0) *(LAS f32x2*)(ob + t * 64 + j0) = (f32x2){oA, oB};
	v_pk_fma_f32 v[46:47], v[26:27], v[46:47], v[66:67]
	v_pk_fma_f32 v[16:17], v[16:17], v[42:43], v[30:31] op_sel:[0,1,0] neg_lo:[0,0,1] neg_hi:[0,0,1]
	v_pk_fma_f32 v[42:43], v[26:27], v[50:51], v[14:15]
	v_pk_fma_f32 v[48:49], v[28:29], v[48:49], v[34:35]
	v_pk_fma_f32 v[52:53], v[28:29], v[52:53], v[16:17]
	s_waitcnt lgkmcnt(8)
	v_pk_mul_f32 v[14:15], v[6:7], v[46:47]
	v_pk_mul_f32 v[6:7], v[6:7], v[42:43]
	v_pk_fma_f32 v[14:15], v[8:9], v[48:49], v[14:15]
	v_pk_fma_f32 v[6:7], v[8:9], v[52:53], v[6:7]
	v_add_f32_e32 v101, v6, v7
	v_add_f32_e32 v100, v14, v15
	s_waitcnt lgkmcnt(3)
	v_pk_mul_f32 v[66:67], v[40:41], v[48:49]
	v_pk_mul_f32 v[40:41], v[40:41], v[52:53]
	v_pk_fma_f32 v[66:67], v[38:39], v[46:47], v[66:67]
	v_pk_fma_f32 v[38:39], v[38:39], v[42:43], v[40:41]
	v_add_f32_e32 v40, v66, v67
	v_add_f32_e32 v39, v38, v39
	ds_read_b128 v[14:17], v97 offset:9216
	ds_read_b128 v[30:33], v97 offset:13312
	ds_read_b128 v[34:37], v97 offset:17408
	ds_read_b64 v[50:51], v98 offset:1024
	ds_read_b128 v[26:29], v97 offset:5120
	ds_read_b128 v[6:9], v97 offset:1024
	v_add_f32_dpp v38, v40, v40 quad_perm:[1,0,3,2] row_mask:0xf bank_mask:0xf bound_ctrl:1
	v_add_f32_dpp v39, v39, v39 quad_perm:[1,0,3,2] row_mask:0xf bank_mask:0xf bound_ctrl:1
	v_add_f32_dpp v100, v100, v100 quad_perm:[1,0,3,2] row_mask:0xf bank_mask:0xf bound_ctrl:1
	v_add_f32_dpp v101, v101, v101 quad_perm:[1,0,3,2] row_mask:0xf bank_mask:0xf bound_ctrl:1
	v_add_f32_dpp v38, v38, v38 quad_perm:[2,3,0,1] row_mask:0xf bank_mask:0xf bound_ctrl:1
	v_add_f32_dpp v39, v39, v39 quad_perm:[2,3,0,1] row_mask:0xf bank_mask:0xf bound_ctrl:1
	v_add_f32_dpp v100, v100, v100 quad_perm:[2,3,0,1] row_mask:0xf bank_mask:0xf bound_ctrl:1
	v_add_f32_dpp v101, v101, v101 quad_perm:[2,3,0,1] row_mask:0xf bank_mask:0xf bound_ctrl:1
	v_add_f32_dpp v38, v38, v38 row_half_mirror row_mask:0xf bank_mask:0xf bound_ctrl:1
	v_add_f32_dpp v39, v39, v39 row_half_mirror row_mask:0xf bank_mask:0xf bound_ctrl:1
	v_add_f32_dpp v100, v100, v100 row_half_mirror row_mask:0xf bank_mask:0xf bound_ctrl:1
	v_add_f32_dpp v101, v101, v101 row_half_mirror row_mask:0xf bank_mask:0xf bound_ctrl:1
	v_add_f32_dpp v38, v38, v38 row_mirror row_mask:0xf bank_mask:0xf bound_ctrl:1
	v_add_f32_dpp v66, v39, v39 row_mirror row_mask:0xf bank_mask:0xf bound_ctrl:1
	v_add_f32_dpp v100, v100, v100 row_mirror row_mask:0xf bank_mask:0xf bound_ctrl:1
	v_add_f32_dpp v101, v101, v101 row_mirror row_mask:0xf bank_mask:0xf bound_ctrl:1
	s_mov_b64 exec, vcc
	ds_write_b64 v96, v[100:101] offset:768
	s_mov_b64 exec, -1
	v_pk_mul_f32 v[40:41], v[22:23], v[38:39] op_sel_hi:[1,0]
	v_pk_mul_f32 v[38:39], v[24:25], v[38:39] op_sel_hi:[1,0]
	v_pk_mul_f32 v[22:23], v[22:23], v[66:67] op_sel_hi:[1,0]
	s_waitcnt lgkmcnt(9)
	v_pk_fma_f32 v[40:41], v[10:11], v[44:45], v[40:41] op_sel_hi:[1,0,1] neg_lo:[0,0,1] neg_hi:[0,0,1]
	v_pk_fma_f32 v[68:69], v[12:13], v[44:45], v[38:39] op_sel_hi:[1,0,1] neg_lo:[0,0,1] neg_hi:[0,0,1]
	v_pk_fma_f32 v[10:11], v[10:11], v[44:45], v[22:23] op_sel:[0,1,0] neg_lo:[0,0,1] neg_hi:[0,0,1]
	v_pk_mul_f32 v[22:23], v[24:25], v[66:67] op_sel_hi:[1,0]
	s_waitcnt lgkmcnt(8)
	v_pk_fma_f32 v[38:39], v[18:19], v[46:47], v[40:41]
	v_pk_fma_f32 v[40:41], v[20:21], v[48:49], v[68:69]
	v_pk_fma_f32 v[12:13], v[12:13], v[44:45], v[22:23] op_sel:[0,1,0] neg_lo:[0,0,1] neg_hi:[0,0,1]
	v_pk_fma_f32 v[68:69], v[18:19], v[42:43], v[10:11]
	v_pk_fma_f32 v[52:53], v[20:21], v[52:53], v[12:13]
	s_waitcnt lgkmcnt(8)
	v_pk_mul_f32 v[10:11], v[2:3], v[38:39]
	v_pk_mul_f32 v[2:3], v[2:3], v[68:69]
	v_pk_fma_f32 v[10:11], v[4:5], v[40:41], v[10:11]
	v_pk_fma_f32 v[2:3], v[4:5], v[52:53], v[2:3]
	v_add_f32_e32 v101, v2, v3
	v_add_f32_e32 v100, v10, v11
	s_waitcnt lgkmcnt(3)
	v_pk_mul_f32 v[2:3], v[36:37], v[40:41]
	v_pk_mul_f32 v[4:5], v[36:37], v[52:53]
	v_pk_fma_f32 v[2:3], v[34:35], v[38:39], v[2:3]
	v_pk_fma_f32 v[4:5], v[34:35], v[68:69], v[4:5]
	v_add_f32_e32 v2, v2, v3
	v_add_f32_e32 v3, v4, v5
	ds_read_b128 v[18:21], v97 offset:9472
	ds_read_b128 v[42:45], v97 offset:13568
	ds_read_b128 v[46:49], v97 offset:17664
	ds_read_b64 v[66:67], v98 offset:1280
	ds_read_b128 v[22:25], v97 offset:5376
	ds_read_b128 v[10:13], v97 offset:1280
	v_add_f32_dpp v2, v2, v2 quad_perm:[1,0,3,2] row_mask:0xf bank_mask:0xf bound_ctrl:1
	v_add_f32_dpp v3, v3, v3 quad_perm:[1,0,3,2] row_mask:0xf bank_mask:0xf bound_ctrl:1
	v_add_f32_dpp v100, v100, v100 quad_perm:[1,0,3,2] row_mask:0xf bank_mask:0xf bound_ctrl:1
	v_add_f32_dpp v101, v101, v101 quad_perm:[1,0,3,2] row_mask:0xf bank_mask:0xf bound_ctrl:1
	v_add_f32_dpp v2, v2, v2 quad_perm:[2,3,0,1] row_mask:0xf bank_mask:0xf bound_ctrl:1
	v_add_f32_dpp v3, v3, v3 quad_perm:[2,3,0,1] row_mask:0xf bank_mask:0xf bound_ctrl:1
	v_add_f32_dpp v100, v100, v100 quad_perm:[2,3,0,1] row_mask:0xf bank_mask:0xf bound_ctrl:1
	v_add_f32_dpp v101, v101, v101 quad_perm:[2,3,0,1] row_mask:0xf bank_mask:0xf bound_ctrl:1
	v_add_f32_dpp v2, v2, v2 row_half_mirror row_mask:0xf bank_mask:0xf bound_ctrl:1
	v_add_f32_dpp v3, v3, v3 row_half_mirror row_mask:0xf bank_mask:0xf bound_ctrl:1
	v_add_f32_dpp v100, v100, v100 row_half_mirror row_mask:0xf bank_mask:0xf bound_ctrl:1
	v_add_f32_dpp v101, v101, v101 row_half_mirror row_mask:0xf bank_mask:0xf bound_ctrl:1
	v_add_f32_dpp v2, v2, v2 row_mirror row_mask:0xf bank_mask:0xf bound_ctrl:1
	v_add_f32_dpp v4, v3, v3 row_mirror row_mask:0xf bank_mask:0xf bound_ctrl:1
	v_add_f32_dpp v100, v100, v100 row_mirror row_mask:0xf bank_mask:0xf bound_ctrl:1
	v_add_f32_dpp v101, v101, v101 row_mirror row_mask:0xf bank_mask:0xf bound_ctrl:1
	s_mov_b64 exec, vcc
	ds_write_b64 v96, v[100:101] offset:1024
	s_mov_b64 exec, -1
	v_pk_mul_f32 v[34:35], v[30:31], v[2:3] op_sel_hi:[1,0]
	v_pk_mul_f32 v[2:3], v[32:33], v[2:3] op_sel_hi:[1,0]
	s_waitcnt lgkmcnt(9)
; #define LAS __attribute__((address_space(3)))
; template <int pass>
; __device__ __forceinline__ void rw_item(const Params& p, int l, int seg, int h, LAS float* sm, int tid, int lane, int wave) {
;     ...
;                 const int tn = (t + 1 < TS) ? t + 1 : t, on = tn * 64 + kq * 4;
;                 nw4 = *(const LAS f32x4*)(bf + 1024 + on); nk4 = *(const LAS f32x4*)(bf + 2048 + on);
;                 na4 = *(const LAS f32x4*)(bf + 3072 + on); nb4 = *(const LAS f32x4*)(bf + 4096 + on);
;                 nvv = *(const LAS f32x2*)(bf + 5120 + tn * 64 + j0);
;                 if (pass == 1) nq4 = *(const LAS f32x4*)(bf + on);
;             }
;             const f32x2 vA = {vv.x, vv.x}, vB = {vv.y, vv.y};
;             f32x2 ua = b4.xy * sA[0], ub = b4.xy * sB[0];
;             ua = b4.zw * sA[1] + ua; ub = b4.zw * sB[1] + ub;
;             float uA = ua.x + ua.y, uB = ub.x + ub.y, gA = 0.f, gB = 0.f;
;             if (pass == 0) {
;                 f32x2 qa = b4.xy * pA[0], qb = b4.xy * pB[0];
;                 qa = b4.zw * pA[1] + qa; qb = b4.zw * pB[1] + qb;
;                 gA = qa.x + qa.y; gB = qb.x + qb.y;
;                 kq_sum16x4(uA, uB, gA, gB);
;             } else { uA = kq_sum<16>(uA); uB = kq_sum<16>(uB); }
;             const f32x2 uA2 = {uA, uA}, uB2 = {uB, uB};
;             { const f32x2 t0_ = k4.xy * vA - a4.xy * uA2, t1_ = k4.zw * vA - a4.zw * uA2; sA[0] = w4.xy * sA[0] + t0_; sA[1] = w4.zw * sA[1] + t1_; }
;             { const f32x2 t0_ = k4.xy * vB - a4.xy * uB2, t1_ = k4.zw * vB - a4.zw * uB2; sB[0] = w4.xy * sB[0] + t0_; sB[1] = w4.zw * sB[1] + t1_; }
;             if (pass == 0) {
;                 const f32x2 gA2 = {gA, gA}, gB2 = {gB, gB};
;                 pA[0] = w4.xy * pA[0] - a4.xy * gA2; pA[1] = w4.zw * pA[1] - a4.zw * gA2;
;                 pB[0] = w4.xy * pB[0] - a4.xy * gB2; pB[1] = w4.zw * pB[1] - a4.zw * gB2;
;             } else {
;                 f32x2 oa = q4.xy * sA[0], ob2 = q4.xy * sB[0];
;                 oa = q4.zw * sA[1] + oa; ob2 = q4.zw * sB[1] + ob2;
;                 const float oA = kq_sum<16>(oa.x + oa.y), oB = kq_sum<16>(ob2.x + ob2.y);
;                 if (kq == 0) *(LAS f32x2*)(ob + t * 64 + j0) = (f32x2){oA, oB};
	v_pk_fma_f32 v[34:35], v[14:15], v[50:51], v[34:35] op_sel_hi:[1,0,1] neg_lo:[0,0,1] neg_hi:[0,0,1]
	v_pk_fma_f32 v[2:3], v[16:17], v[50:51], v[2:3] op_sel_hi:[1,0,1] neg_lo:[0,0,1] neg_hi:[0,0,1]
	s_waitcnt lgkmcnt(8)
	v_pk_fma_f32 v[70:71], v[26:27], v[38:39], v[34:35]
	v_pk_fma_f32 v[72:73], v[28:29], v[40:41], v[2:3]
	v_pk_mul_f32 v[2:3], v[30:31], v[4:5] op_sel_hi:[1,0]
	v_pk_mul_f32 v[4:5], v[32:33], v[4:5] op_sel_hi:[1,0]
	v_pk_fma_f32 v[2:3], v[14:15], v[50:51], v[2:3] op_sel:[0,1,0] neg_lo:[0,0,1] neg_hi:[0,0,1]
	v_pk_fma_f32 v[4:5], v[16:17], v[50:51], v[4:5] op_sel:[0,1,0] neg_lo:[0,0,1] neg_hi:[0,0,1]
	v_pk_fma_f32 v[14:15], v[26:27], v[68:69], v[2:3]
	v_pk_fma_f32 v[16:17], v[28:29], v[52:53], v[4:5]
	s_waitcnt lgkmcnt(8)
	v_pk_mul_f32 v[2:3], v[6:7], v[70:71]
	v_pk_mul_f32 v[4:5], v[6:7], v[14:15]
	v_pk_fma_f32 v[2:3], v[8:9], v[72:73], v[2:3]
	v_pk_fma_f32 v[4:5], v[8:9], v[16:17], v[4:5]
	v_add_f32_e32 v100, v2, v3
	v_add_f32_e32 v101, v4, v5
	s_waitcnt lgkmcnt(3)
	v_pk_mul_f32 v[26:27], v[48:49], v[72:73]
	v_pk_mul_f32 v[28:29], v[48:49], v[16:17]
	v_pk_fma_f32 v[26:27], v[46:47], v[70:71], v[26:27]
	v_pk_fma_f32 v[28:29], v[46:47], v[14:15], v[28:29]
	v_add_f32_e32 v26, v26, v27
	v_add_f32_e32 v27, v28, v29
	ds_read_b128 v[2:5], v97 offset:9728
	ds_read_b128 v[38:41], v97 offset:13824
	ds_read_b128 v[6:9], v97 offset:17920
	ds_read_b64 v[52:53], v98 offset:1536
	ds_read_b128 v[34:37], v97 offset:5632
	ds_read_b128 v[30:33], v97 offset:1536
	v_add_f32_dpp v26, v26, v26 quad_perm:[1,0,3,2] row_mask:0xf bank_mask:0xf bound_ctrl:1
	v_add_f32_dpp v27, v27, v27 quad_perm:[1,0,3,2] row_mask:0xf bank_mask:0xf bound_ctrl:1
	v_add_f32_dpp v100, v100, v100 quad_perm:[1,0,3,2] row_mask:0xf bank_mask:0xf bound_ctrl:1
	v_add_f32_dpp v101, v101, v101 quad_perm:[1,0,3,2] row_mask:0xf bank_mask:0xf bound_ctrl:1
	v_add_f32_dpp v26, v26, v26 quad_perm:[2,3,0,1] row_mask:0xf bank_mask:0xf bound_ctrl:1
	v_add_f32_dpp v27, v27, v27 quad_perm:[2,3,0,1] row_mask:0xf bank_mask:0xf bound_ctrl:1
	v_add_f32_dpp v100, v100, v100 quad_perm:[2,3,0,1] row_mask:0xf bank_mask:0xf bound_ctrl:1
	v_add_f32_dpp v101, v101, v101 quad_perm:[2,3,0,1] row_mask:0xf bank_mask:0xf bound_ctrl:1
	v_add_f32_dpp v26, v26, v26 row_half_mirror row_mask:0xf bank_mask:0xf bound_ctrl:1
	v_add_f32_dpp v27, v27, v27 row_half_mirror row_mask:0xf bank_mask:0xf bound_ctrl:1
	v_add_f32_dpp v100, v100, v100 row_half_mirror row_mask:0xf bank_mask:0xf bound_ctrl:1
	v_add_f32_dpp v101, v101, v101 row_half_mirror row_mask:0xf bank_mask:0xf bound_ctrl:1
	v_add_f32_dpp v26, v26, v26 row_mirror row_mask:0xf bank_mask:0xf bound_ctrl:1
	v_add_f32_dpp v28, v27, v27 row_mirror row_mask:0xf bank_mask:0xf bound_ctrl:1
	v_add_f32_dpp v100, v100, v100 row_mirror row_mask:0xf bank_mask:0xf bound_ctrl:1
	v_add_f32_dpp v101, v101, v101 row_mirror row_mask:0xf bank_mask:0xf bound_ctrl:1
	s_mov_b64 exec, vcc
	ds_write_b64 v96, v[100:101] offset:1280
	s_mov_b64 exec, -1
	v_pk_mul_f32 v[46:47], v[42:43], v[26:27] op_sel_hi:[1,0]
	v_pk_mul_f32 v[26:27], v[44:45], v[26:27] op_sel_hi:[1,0]
	s_waitcnt lgkmcnt(9)
	v_pk_fma_f32 v[46:47], v[18:19], v[66:67], v[46:47] op_sel_hi:[1,0,1] neg_lo:[0,0,1] neg_hi:[0,0,1]
	v_pk_fma_f32 v[26:27], v[20:21], v[66:67], v[26:27] op_sel_hi:[1,0,1] neg_lo:[0,0,1] neg_hi:[0,0,1]
	s_waitcnt lgkmcnt(8)
	v_pk_fma_f32 v[46:47], v[22:23], v[70:71], v[46:47]
	v_pk_fma_f32 v[48:49], v[24:25], v[72:73], v[26:27]
	v_pk_mul_f32 v[26:27], v[42:43], v[28:29] op_sel_hi:[1,0]
	s_nop 0
	v_pk_fma_f32 v[18:19], v[18:19], v[66:67], v[26:27] op_sel:[0,1,0] neg_lo:[0,0,1] neg_hi:[0,0,1]
	v_pk_mul_f32 v[26:27], v[44:45], v[28:29] op_sel_hi:[1,0]
	v_pk_fma_f32 v[42:43], v[22:23], v[14:15], v[18:19]
	v_pk_fma_f32 v[20:21], v[20:21], v[66:67], v[26:27] op_sel:[0,1,0] neg_lo:[0,0,1] neg_hi:[0,0,1]
	s_waitcnt lgkmcnt(8)
	v_pk_mul_f32 v[14:15], v[10:11], v[46:47]
	v_pk_fma_f32 v[44:45], v[24:25], v[16:17], v[20:21]
	v_pk_mul_f32 v[10:11], v[10:11], v[42:43]
	v_pk_fma_f32 v[14:15], v[12:13], v[48:49], v[14:15]
	v_pk_fma_f32 v[10:11], v[12:13], v[44:45], v[10:11]
	v_add_f32_e32 v101, v10, v11
	v_add_f32_e32 v100, v14, v15
	s_waitcnt lgkmcnt(3)
; #define LAS __attribute__((address_space(3)))
; template <int pass>
; __device__ __forceinline__ void rw_item(const Params& p, int l, int seg, int h, LAS float* sm, int tid, int lane, int wave) {
;     ...
;         for (int t = 0; t < TS; ++t) {
;             const f32x4 w4 = nw4, k4 = nk4, a4 = na4, b4 = nb4, q4 = nq4; const f32x2 vv = nvv;
;             {
;                 const int tn = (t + 1 < TS) ? t + 1 : t, on = tn * 64 + kq * 4;
;                 nw4 = *(const LAS f32x4*)(bf + 1024 + on); nk4 = *(const LAS f32x4*)(bf + 2048 + on);
;                 na4 = *(const LAS f32x4*)(bf + 3072 + on); nb4 = *(const LAS f32x4*)(bf + 4096 + on);
;                 nvv = *(const LAS f32x2*)(bf + 5120 + tn * 64 + j0);
;                 if (pass == 1) nq4 = *(const LAS f32x4*)(bf + on);
;             }
;             const f32x2 vA = {vv.x, vv.x}, vB = {vv.y, vv.y};
;             f32x2 ua = b4.xy * sA[0], ub = b4.xy * sB[0];
;             ua = b4.zw * sA[1] + ua; ub = b4.zw * sB[1] + ub;
;             float uA = ua.x + ua.y, uB = ub.x + ub.y, gA = 0.f, gB = 0.f;
;             if (pass == 0) {
;                 f32x2 qa = b4.xy * pA[0], qb = b4.xy * pB[0];
;                 qa = b4.zw * pA[1] + qa; qb = b4.zw * pB[1] + qb;
;                 gA = qa.x + qa.y; gB = qb.x + qb.y;
;                 kq_sum16x4(uA, uB, gA, gB);
;             } else { uA = kq_sum<16>(uA); uB = kq_sum<16>(uB); }
;             const f32x2 uA2 = {uA, uA}, uB2 = {uB, uB};
;             { const f32x2 t0_ = k4.xy * vA - a4.xy * uA2, t1_ = k4.zw * vA - a4.zw * uA2; sA[0] = w4.xy * sA[0] + t0_; sA[1] = w4.zw * sA[1] + t1_; }
;             { const f32x2 t0_ = k4.xy * vB - a4.xy * uB2, t1_ = k4.zw * vB - a4.zw * uB2; sB[0] = w4.xy * sB[0] + t0_; sB[1] = w4.zw * sB[1] + t1_; }
;             if (pass == 0) {
;                 const f32x2 gA2 = {gA, gA}, gB2 = {gB, gB};
;                 pA[0] = w4.xy * pA[0] - a4.xy * gA2; pA[1] = w4.zw * pA[1] - a4.zw * gA2;
;                 pB[0] = w4.xy * pB[0] - a4.xy * gB2; pB[1] = w4.zw * pB[1] - a4.zw * gB2;
;             } else {
;                 f32x2 oa = q4.xy * sA[0], ob2 = q4.xy * sB[0];
;                 oa = q4.zw * sA[1] + oa; ob2 = q4.zw * sB[1] + ob2;
;                 const float oA = kq_sum<16>(oa.x + oa.y), oB = kq_sum<16>(ob2.x + ob2.y);
;                 if (kq == 0) *(LAS f32x2*)(ob + t * 64 + j0) = (f32x2){oA, oB};
;             }
	v_pk_mul_f32 v[66:67], v[8:9], v[48:49]
	v_pk_mul_f32 v[8:9], v[8:9], v[44:45]
	v_pk_fma_f32 v[66:67], v[6:7], v[46:47], v[66:67]
	v_pk_fma_f32 v[6:7], v[6:7], v[42:43], v[8:9]
	v_add_f32_e32 v8, v66, v67
	v_add_f32_e32 v7, v6, v7
	s_cmpk_lg_i32 s38, 0x800
	v_add_f32_dpp v6, v8, v8 quad_perm:[1,0,3,2] row_mask:0xf bank_mask:0xf bound_ctrl:1
	v_add_f32_dpp v7, v7, v7 quad_perm:[1,0,3,2] row_mask:0xf bank_mask:0xf bound_ctrl:1
	v_add_f32_dpp v100, v100, v100 quad_perm:[1,0,3,2] row_mask:0xf bank_mask:0xf bound_ctrl:1
	v_add_f32_dpp v101, v101, v101 quad_perm:[1,0,3,2] row_mask:0xf bank_mask:0xf bound_ctrl:1
	s_cselect_b32 s0, s37, 0x3c0
	v_add_f32_dpp v6, v6, v6 quad_perm:[2,3,0,1] row_mask:0xf bank_mask:0xf bound_ctrl:1
	v_add_f32_dpp v7, v7, v7 quad_perm:[2,3,0,1] row_mask:0xf bank_mask:0xf bound_ctrl:1
	v_add_f32_dpp v100, v100, v100 quad_perm:[2,3,0,1] row_mask:0xf bank_mask:0xf bound_ctrl:1
	v_add_f32_dpp v101, v101, v101 quad_perm:[2,3,0,1] row_mask:0xf bank_mask:0xf bound_ctrl:1
	v_or_b32_e32 v10, s0, v0
	v_add_f32_dpp v6, v6, v6 row_half_mirror row_mask:0xf bank_mask:0xf bound_ctrl:1
	v_add_f32_dpp v7, v7, v7 row_half_mirror row_mask:0xf bank_mask:0xf bound_ctrl:1
	v_add_f32_dpp v100, v100, v100 row_half_mirror row_mask:0xf bank_mask:0xf bound_ctrl:1
	v_add_f32_dpp v101, v101, v101 row_half_mirror row_mask:0xf bank_mask:0xf bound_ctrl:1
	v_lshl_add_u32 v22, v10, 2, s5
	v_add_f32_dpp v6, v6, v6 row_mirror row_mask:0xf bank_mask:0xf bound_ctrl:1
	v_add_f32_dpp v66, v7, v7 row_mirror row_mask:0xf bank_mask:0xf bound_ctrl:1
	v_add_f32_dpp v100, v100, v100 row_mirror row_mask:0xf bank_mask:0xf bound_ctrl:1
	v_add_f32_dpp v101, v101, v101 row_mirror row_mask:0xf bank_mask:0xf bound_ctrl:1
	s_mov_b64 exec, vcc
	ds_write_b64 v96, v[100:101] offset:1536
	s_mov_b64 exec, -1
	v_pk_mul_f32 v[8:9], v[38:39], v[6:7] op_sel_hi:[1,0]
	v_pk_mul_f32 v[38:39], v[38:39], v[66:67] op_sel_hi:[1,0]
	s_waitcnt lgkmcnt(3)
	v_pk_fma_f32 v[8:9], v[2:3], v[52:53], v[8:9] op_sel_hi:[1,0,1] neg_lo:[0,0,1] neg_hi:[0,0,1]
	v_pk_mul_f32 v[6:7], v[40:41], v[6:7] op_sel_hi:[1,0]
	v_pk_fma_f32 v[2:3], v[2:3], v[52:53], v[38:39] op_sel:[0,1,0] neg_lo:[0,0,1] neg_hi:[0,0,1]
	v_pk_mul_f32 v[38:39], v[40:41], v[66:67] op_sel_hi:[1,0]
	v_pk_fma_f32 v[68:69], v[4:5], v[52:53], v[6:7] op_sel_hi:[1,0,1] neg_lo:[0,0,1] neg_hi:[0,0,1]
	s_waitcnt lgkmcnt(2)
	v_pk_fma_f32 v[6:7], v[34:35], v[46:47], v[8:9]
	v_pk_fma_f32 v[4:5], v[4:5], v[52:53], v[38:39] op_sel:[0,1,0] neg_lo:[0,0,1] neg_hi:[0,0,1]
	v_pk_fma_f32 v[2:3], v[34:35], v[42:43], v[2:3]
	v_pk_fma_f32 v[8:9], v[36:37], v[48:49], v[68:69]
	v_pk_fma_f32 v[4:5], v[36:37], v[44:45], v[4:5]
	s_waitcnt lgkmcnt(2)
	v_pk_mul_f32 v[34:35], v[30:31], v[6:7]
	v_pk_mul_f32 v[30:31], v[30:31], v[2:3]
	v_pk_fma_f32 v[34:35], v[32:33], v[8:9], v[34:35]
	v_pk_fma_f32 v[30:31], v[32:33], v[4:5], v[30:31]
	v_add_f32_e32 v31, v30, v31
	v_add_f32_e32 v30, v34, v35
	v_lshl_add_u32 v10, s0, 2, v93
	ds_read_b128 v[14:17], v22 offset:8192
	ds_read_b128 v[18:21], v22 offset:12288
	ds_read_b128 v[26:29], v22 offset:16384
	ds_read_b64 v[50:51], v10 offset:20480
	ds_read_b128 v[10:13], v22 offset:4096
	ds_read_b128 v[22:25], v22
	v_add_f32_dpp v30, v30, v30 quad_perm:[1,0,3,2] row_mask:0xf bank_mask:0xf bound_ctrl:1
	v_add_f32_dpp v31, v31, v31 quad_perm:[1,0,3,2] row_mask:0xf bank_mask:0xf bound_ctrl:1
	s_nop 0
	v_add_f32_dpp v30, v30, v30 quad_perm:[2,3,0,1] row_mask:0xf bank_mask:0xf bound_ctrl:1
	v_add_f32_dpp v31, v31, v31 quad_perm:[2,3,0,1] row_mask:0xf bank_mask:0xf bound_ctrl:1
	s_nop 0
	v_add_f32_dpp v30, v30, v30 row_half_mirror row_mask:0xf bank_mask:0xf bound_ctrl:1
	v_add_f32_dpp v31, v31, v31 row_half_mirror row_mask:0xf bank_mask:0xf bound_ctrl:1
	s_nop 0
	v_add_f32_dpp v30, v30, v30 row_mirror row_mask:0xf bank_mask:0xf bound_ctrl:1
	v_add_f32_dpp v31, v31, v31 row_mirror row_mask:0xf bank_mask:0xf bound_ctrl:1
	s_and_saveexec_b64 s[0:1], vcc
	s_cbranch_execz .LBB0_456
	ds_write_b64 v96, v[30:31] offset:1792
	s_branch .LBB0_456
